# unit A softmax: 90 packed fp32 VOP3P ops in the MFMA shadow split into single VOP2 ops (asm guide 7.5), on top of v35
# baseline (speedup 1.0000x reference)
; __device__ __forceinline__ unsigned pk2(float lo, float hi) { return pg8::cvt_pk_bf16(lo, hi); }
; template <int RANGE>
; __device__ __forceinline__ void a_softmax(f32x16 s, int tt, int P0, int qpos, int lane, const float (&wp)[16], bf16x8& pf0, bf16x8& pf1, float& lsum) {
;     constexpr int ST = RANGE == 3 ? 8 : (RANGE == 2 ? 4 : 1);
;     int kbase, stride; a_tile_desc(tt, P0, kbase, stride);
;     const int hi = lane >> 5;
;     const int d0 = qpos - kbase - ST * 4 * hi;
;     const int lim3 = qpos < 2048 ? qpos : 2048;
;     float ps = 0.f;
; #pragma unroll
;     for (int r = 0; r < 16; ++r) { const int delta = d0 - ST * ((r & 3) + 8 * (r >> 2)); float w;
;         if (RANGE == 1) w = ((unsigned)delta <= (unsigned)qpos) ? wp[r] + (delta <= 128 ? 1.f : 0.f) : 0.f;
;         else if (RANGE == 2) w = (delta <= qpos) ? wp[r] + (delta <= 512 ? 1.f : 0.f) : 0.f;
;         else w = (delta <= lim3) ? wp[r] : 0.f;
;         const float p = w * __builtin_amdgcn_exp2f(s[r]); ps += p; s[r] = p; }
;     lsum += ps;
;     v4u pa, pb; pa.x = pk2(s[0], s[1]); pa.y = pk2(s[2], s[3]); pa.z = pk2(s[4], s[5]); pa.w = pk2(s[6], s[7]); pb.x = pk2(s[8], s[9]); pb.y = pk2(s[10], s[11]); pb.z = pk2(s[12], s[13]); pb.w = pk2(s[14], s[15]);
;     pf0 = __builtin_bit_cast(bf16x8, pa); pf1 = __builtin_bit_cast(bf16x8, pb);
; }
.LBB0_692:
	v_exp_f32_e32 v111, v68
	v_exp_f32_e32 v110, v69
	v_exp_f32_e32 v109, v70
	v_exp_f32_e32 v108, v71
	v_exp_f32_e32 v106, v72
	v_exp_f32_e32 v107, v73
	v_exp_f32_e32 v104, v74
	v_exp_f32_e32 v105, v75
	v_exp_f32_e32 v102, v76
	v_exp_f32_e32 v103, v77
	v_exp_f32_e32 v100, v78
	v_exp_f32_e32 v101, v79
	v_exp_f32_e32 v78, v80
	v_exp_f32_e32 v79, v81
	v_exp_f32_e32 v76, v82
	v_exp_f32_e32 v77, v83
	s_cmp_lt_u32 s73, 9
	s_cselect_b64 s[34:35], -1, 0
	s_cmp_gt_i32 s36, 2
	s_mov_b64 s[2:3], -1
	s_cbranch_scc0 .LBB0_694
	s_and_b64 s[2:3], s[34:35], exec
	s_cselect_b32 s37, 0xffffff80, s91
	s_cselect_b32 s38, 0x500, s0
	s_and_b64 s[2:3], s[12:13], exec
	s_cselect_b32 s2, 0xffffff00, s37
	s_cselect_b32 s3, 0x800, s38
	s_mul_i32 s2, s2, s73
	s_add_i32 s2, s2, s3
	v_add_u32_e32 v2, s2, v237
	v_cmp_le_i32_e32 vcc, v2, v198
	v_add_u32_e32 v68, -8, v2
	v_add_u32_e32 v69, 0xffffffb8, v2
	v_cndmask_b32_e32 v112, 0, v36, vcc
	v_cmp_le_i32_e32 vcc, v68, v198
	v_add_u32_e32 v68, -16, v2
	v_mul_f32_e32 v243, v111, v112
	v_cndmask_b32_e32 v113, 0, v37, vcc
	v_cmp_le_i32_e32 vcc, v68, v198
	v_subrev_u32_e32 v68, 24, v2
	v_mul_f32_e32 v244, v110, v113
	v_cndmask_b32_e32 v114, 0, v38, vcc
	v_cmp_le_i32_e32 vcc, v68, v198
	v_subrev_u32_e32 v68, 64, v2
	v_mul_f32_e32 v245, v109, v114
	v_cndmask_b32_e32 v115, 0, v39, vcc
	v_cmp_le_i32_e32 vcc, v69, v1
	v_mul_f32_e32 v246, v108, v115
	s_mov_b64 s[2:3], 0
	v_cndmask_b32_e32 v69, 0, v41, vcc
	v_cmp_le_i32_e32 vcc, v68, v198
	s_nop 1
	v_cndmask_b32_e32 v68, 0, v40, vcc
	v_mul_f32_e32 v70, v106, v68
	v_mul_f32_e32 v71, v107, v69
	v_add_u32_e32 v69, 0xffffffa8, v2
	v_add_u32_e32 v68, 0xffffffb0, v2
	v_cmp_le_i32_e32 vcc, v69, v1
	s_nop 1
	v_cndmask_b32_e32 v69, 0, v43, vcc
	v_cmp_le_i32_e32 vcc, v68, v198
	s_nop 1
	v_cndmask_b32_e32 v68, 0, v42, vcc
	v_mul_f32_e32 v72, v104, v68
	v_mul_f32_e32 v73, v105, v69
	v_add_u32_e32 v69, 0xffffff78, v2
	v_add_u32_e32 v68, 0xffffff80, v2
	v_cmp_le_i32_e32 vcc, v69, v1
	s_nop 1
	v_cndmask_b32_e32 v69, 0, v45, vcc
	v_cmp_le_i32_e32 vcc, v68, v198
	s_nop 1
	v_cndmask_b32_e32 v68, 0, v44, vcc
	v_mul_f32_e32 v74, v102, v68
	v_mul_f32_e32 v75, v103, v69
	v_add_u32_e32 v69, 0xffffff68, v2
	v_add_u32_e32 v68, 0xffffff70, v2
	v_cmp_le_i32_e32 vcc, v69, v1
	s_nop 1
	v_cndmask_b32_e32 v69, 0, v47, vcc
	v_cmp_le_i32_e32 vcc, v68, v198
	s_nop 1
	v_cndmask_b32_e32 v68, 0, v46, vcc
	v_mul_f32_e32 v80, v100, v68
	v_mul_f32_e32 v81, v101, v69
	v_add_u32_e32 v69, 0xffffff38, v2
	v_add_u32_e32 v68, 0xffffff40, v2
	v_cmp_le_i32_e32 vcc, v69, v1
	s_nop 1
	v_cndmask_b32_e32 v69, 0, v49, vcc
	v_cmp_le_i32_e32 vcc, v68, v198
	s_nop 1
	v_cndmask_b32_e32 v68, 0, v48, vcc
	v_mul_f32_e32 v82, v78, v68
	v_mul_f32_e32 v83, v79, v69
	v_fma_f32 v68, v111, v112, 0
	v_fmac_f32_e32 v68, v110, v113
	v_fmac_f32_e32 v68, v109, v114
	v_fmac_f32_e32 v68, v108, v115
	v_add_f32_e32 v68, v70, v68
	v_add_f32_e32 v68, v71, v68
	v_add_f32_e32 v68, v72, v68
	v_add_f32_e32 v68, v73, v68
	v_add_f32_e32 v68, v74, v68
	v_add_f32_e32 v68, v75, v68
	v_add_f32_e32 v68, v80, v68
	v_add_f32_e32 v68, v81, v68
	v_add_f32_e32 v68, v82, v68
	v_add_f32_e32 v114, v83, v68
	v_add_u32_e32 v68, 0xffffff30, v2
	v_add_u32_e32 v2, 0xffffff28, v2
	v_cmp_le_i32_e32 vcc, v2, v1
	s_nop 1
	v_cndmask_b32_e32 v69, 0, v51, vcc
	v_cmp_le_i32_e32 vcc, v68, v198
	s_nop 1
	v_cndmask_b32_e32 v68, 0, v50, vcc
	v_mul_f32_e32 v112, v76, v68
	v_mul_f32_e32 v113, v77, v69
	v_cvt_pk_bf16_f32 v68, v243, v244
	v_cvt_pk_bf16_f32 v69, v245, v246
	v_cvt_pk_bf16_f32 v70, v70, v71
	v_cvt_pk_bf16_f32 v71, v72, v73
	v_cvt_pk_bf16_f32 v72, v74, v75
	s_nop 0
	v_add_f32_e32 v2, v112, v114
	v_add_f32_e32 v2, v113, v2
	v_cvt_pk_bf16_f32 v73, v80, v81
	v_cvt_pk_bf16_f32 v74, v82, v83
	v_cvt_pk_bf16_f32 v75, v112, v113
.LBB0_694:
	s_andn2_b64 vcc, exec, s[2:3]
	s_cbranch_vccnz .LBB0_699
	s_cmp_lg_u32 s36, 2
	s_mov_b64 s[2:3], -1
	s_cbranch_scc0 .LBB0_697
	s_and_b64 s[2:3], s[34:35], exec
	s_cselect_b32 s36, 7, 5
	s_cselect_b32 s37, s77, s76
	s_and_b64 s[2:3], s[12:13], exec
	s_cselect_b32 s2, 8, s36
	s_cselect_b32 s3, s72, s37
	s_lshl_b32 s2, s73, s2
	s_add_i32 s2, s2, s3
	v_add_u32_e32 v2, s2, v232
	v_sub_co_u32_e32 v68, vcc, v198, v2
	v_cmp_gt_u32_e64 s[2:3], s1, v68
	v_add_u32_e32 v71, 9, v2
	v_add_u32_e32 v70, 8, v2
	v_cndmask_b32_e64 v68, 0, 1.0, s[2:3]
	v_add_f32_e32 v68, v68, v36
	v_cndmask_b32_e64 v112, v68, 0, vcc
	v_add_u32_e32 v68, 1, v2
	v_sub_co_u32_e32 v68, vcc, v198, v68
	v_cmp_gt_u32_e64 s[2:3], s1, v68
	v_sub_u32_e32 v72, v198, v70
	v_add_u32_e32 v73, 11, v2
	v_cndmask_b32_e64 v68, 0, 1.0, s[2:3]
	v_add_f32_e32 v68, v68, v37
	v_cndmask_b32_e64 v113, v68, 0, vcc
	v_add_u32_e32 v68, 2, v2
	v_sub_co_u32_e32 v68, vcc, v198, v68
	v_cmp_gt_u32_e64 s[2:3], s1, v68
	v_add_u32_e32 v75, 17, v2
	v_add_u32_e32 v81, 19, v2
	v_cndmask_b32_e64 v68, 0, 1.0, s[2:3]
	v_add_f32_e32 v68, v68, v38
	v_cndmask_b32_e64 v114, v68, 0, vcc
	v_add_u32_e32 v68, 3, v2
	v_sub_co_u32_e32 v68, vcc, v198, v68
	v_cmp_gt_u32_e64 s[2:3], s1, v68
	v_add_u32_e32 v83, 25, v2
	v_mul_f32_e32 v243, v111, v112
	v_cndmask_b32_e64 v68, 0, 1.0, s[2:3]
	v_add_f32_e32 v68, v68, v39
	v_cndmask_b32_e64 v115, v68, 0, vcc
	v_sub_u32_e32 v68, v1, v71
	v_cmp_gt_u32_e32 vcc, s1, v68
	v_mul_f32_e32 v245, v109, v114
	v_mul_f32_e32 v244, v110, v113
	v_cndmask_b32_e64 v69, 0, 1.0, vcc
	v_cmp_gt_u32_e32 vcc, s1, v72
	v_add_u32_e32 v72, 10, v2
	v_sub_u32_e32 v74, v198, v72
	v_cndmask_b32_e64 v68, 0, 1.0, vcc
	v_add_f32_e32 v68, v68, v40
	v_add_f32_e32 v69, v69, v41
	v_cmp_ge_u32_e32 vcc, v1, v71
	v_mul_f32_e32 v246, v108, v115
	s_mov_b64 s[2:3], 0
	v_cndmask_b32_e32 v69, 0, v69, vcc
	v_cmp_ge_u32_e32 vcc, v198, v70
; __device__ __forceinline__ unsigned pk2(float lo, float hi) { return pg8::cvt_pk_bf16(lo, hi); }
; template <int RANGE>
; __device__ __forceinline__ void a_softmax(f32x16 s, int tt, int P0, int qpos, int lane, const float (&wp)[16], bf16x8& pf0, bf16x8& pf1, float& lsum) {
;     ...
;     for (int r = 0; r < 16; ++r) { const int delta = d0 - ST * ((r & 3) + 8 * (r >> 2)); float w;
;         if (RANGE == 1) w = ((unsigned)delta <= (unsigned)qpos) ? wp[r] + (delta <= 128 ? 1.f : 0.f) : 0.f;
;         else if (RANGE == 2) w = (delta <= qpos) ? wp[r] + (delta <= 512 ? 1.f : 0.f) : 0.f;
;         else w = (delta <= lim3) ? wp[r] : 0.f;
;         const float p = w * __builtin_amdgcn_exp2f(s[r]); ps += p; s[r] = p; }
;     lsum += ps;
;     v4u pa, pb; pa.x = pk2(s[0], s[1]); pa.y = pk2(s[2], s[3]); pa.z = pk2(s[4], s[5]); pa.w = pk2(s[6], s[7]); pb.x = pk2(s[8], s[9]); pb.y = pk2(s[10], s[11]); pb.z = pk2(s[12], s[13]); pb.w = pk2(s[14], s[15]);
;     pf0 = __builtin_bit_cast(bf16x8, pa); pf1 = __builtin_bit_cast(bf16x8, pb);
	s_nop 1
	v_cndmask_b32_e32 v68, 0, v68, vcc
	v_mul_f32_e32 v70, v106, v68
	v_mul_f32_e32 v71, v107, v69
	v_sub_u32_e32 v68, v1, v73
	v_cmp_gt_u32_e32 vcc, s1, v68
	s_nop 1
	v_cndmask_b32_e64 v69, 0, 1.0, vcc
	v_cmp_gt_u32_e32 vcc, s1, v74
	v_add_u32_e32 v74, 16, v2
	v_sub_u32_e32 v80, v198, v74
	v_cndmask_b32_e64 v68, 0, 1.0, vcc
	v_add_f32_e32 v68, v68, v42
	v_add_f32_e32 v69, v69, v43
	v_cmp_ge_u32_e32 vcc, v1, v73
	s_nop 1
	v_cndmask_b32_e32 v69, 0, v69, vcc
	v_cmp_ge_u32_e32 vcc, v198, v72
	s_nop 1
	v_cndmask_b32_e32 v68, 0, v68, vcc
	v_mul_f32_e32 v72, v104, v68
	v_mul_f32_e32 v73, v105, v69
	v_sub_u32_e32 v68, v1, v75
	v_cmp_gt_u32_e32 vcc, s1, v68
	s_nop 1
	v_cndmask_b32_e64 v69, 0, 1.0, vcc
	v_cmp_gt_u32_e32 vcc, s1, v80
	v_add_u32_e32 v80, 18, v2
	v_sub_u32_e32 v82, v198, v80
	v_cndmask_b32_e64 v68, 0, 1.0, vcc
	v_add_f32_e32 v68, v68, v44
	v_add_f32_e32 v69, v69, v45
	v_cmp_ge_u32_e32 vcc, v1, v75
	s_nop 1
	v_cndmask_b32_e32 v69, 0, v69, vcc
	v_cmp_ge_u32_e32 vcc, v198, v74
	s_nop 1
	v_cndmask_b32_e32 v68, 0, v68, vcc
	v_mul_f32_e32 v74, v102, v68
	v_mul_f32_e32 v75, v103, v69
	v_sub_u32_e32 v68, v1, v81
	v_cmp_gt_u32_e32 vcc, s1, v68
	s_nop 1
	v_cndmask_b32_e64 v69, 0, 1.0, vcc
	v_cmp_gt_u32_e32 vcc, s1, v82
	v_add_u32_e32 v82, 24, v2
	v_sub_u32_e32 v247, v198, v82
	v_cndmask_b32_e64 v68, 0, 1.0, vcc
	v_add_f32_e32 v68, v68, v46
	v_add_f32_e32 v69, v69, v47
	v_cmp_ge_u32_e32 vcc, v1, v81
	s_nop 1
	v_cndmask_b32_e32 v69, 0, v69, vcc
	v_cmp_ge_u32_e32 vcc, v198, v80
	s_nop 1
	v_cndmask_b32_e32 v68, 0, v68, vcc
	v_mul_f32_e32 v80, v100, v68
	v_mul_f32_e32 v81, v101, v69
	v_sub_u32_e32 v68, v1, v83
	v_cmp_gt_u32_e32 vcc, s1, v68
	s_nop 1
	v_cndmask_b32_e64 v69, 0, 1.0, vcc
	v_cmp_gt_u32_e32 vcc, s1, v247
	s_nop 1
	v_cndmask_b32_e64 v68, 0, 1.0, vcc
	v_add_f32_e32 v68, v68, v48
	v_add_f32_e32 v69, v69, v49
	v_cmp_ge_u32_e32 vcc, v1, v83
	s_nop 1
	v_cndmask_b32_e32 v69, 0, v69, vcc
	v_cmp_ge_u32_e32 vcc, v198, v82
	s_nop 1
	v_cndmask_b32_e32 v68, 0, v68, vcc
	v_mul_f32_e32 v82, v78, v68
	v_mul_f32_e32 v83, v79, v69
	v_fma_f32 v68, v111, v112, 0
	v_fmac_f32_e32 v68, v110, v113
	v_fmac_f32_e32 v68, v109, v114
	v_fmac_f32_e32 v68, v108, v115
	v_add_f32_e32 v68, v70, v68
	v_add_f32_e32 v68, v71, v68
	v_add_f32_e32 v68, v72, v68
	v_add_f32_e32 v68, v73, v68
	v_add_f32_e32 v68, v74, v68
	v_add_f32_e32 v68, v75, v68
	v_add_f32_e32 v68, v80, v68
	v_add_f32_e32 v68, v81, v68
	v_add_f32_e32 v68, v82, v68
	v_add_u32_e32 v112, 26, v2
	v_add_u32_e32 v2, 27, v2
	v_add_f32_e32 v114, v83, v68
	v_sub_u32_e32 v68, v1, v2
	v_sub_u32_e32 v113, v198, v112
	v_cmp_gt_u32_e32 vcc, s1, v68
	s_nop 1
	v_cndmask_b32_e64 v69, 0, 1.0, vcc
	v_cmp_gt_u32_e32 vcc, s1, v113
	s_nop 1
	v_cndmask_b32_e64 v68, 0, 1.0, vcc
	v_add_f32_e32 v68, v68, v50
	v_add_f32_e32 v69, v69, v51
	v_cmp_ge_u32_e32 vcc, v1, v2
	s_nop 1
	v_cndmask_b32_e32 v69, 0, v69, vcc
	v_cmp_ge_u32_e32 vcc, v198, v112
	s_nop 1
	v_cndmask_b32_e32 v68, 0, v68, vcc
	v_mul_f32_e32 v112, v76, v68
	v_mul_f32_e32 v113, v77, v69
	v_cvt_pk_bf16_f32 v68, v243, v244
	v_cvt_pk_bf16_f32 v69, v245, v246
	v_cvt_pk_bf16_f32 v70, v70, v71
	v_cvt_pk_bf16_f32 v71, v72, v73
	v_cvt_pk_bf16_f32 v72, v74, v75
	s_nop 0
	v_add_f32_e32 v2, v112, v114
	v_add_f32_e32 v2, v113, v2
	v_cvt_pk_bf16_f32 v73, v80, v81
	v_cvt_pk_bf16_f32 v74, v82, v83
	v_cvt_pk_bf16_f32 v75, v112, v113
; __device__ __forceinline__ unsigned pk2(float lo, float hi) { return pg8::cvt_pk_bf16(lo, hi); }
; template <int RANGE>
; __device__ __forceinline__ void a_softmax(f32x16 s, int tt, int P0, int qpos, int lane, const float (&wp)[16], bf16x8& pf0, bf16x8& pf1, float& lsum) {
;     ...
;     for (int r = 0; r < 16; ++r) { const int delta = d0 - ST * ((r & 3) + 8 * (r >> 2)); float w;
;         if (RANGE == 1) w = ((unsigned)delta <= (unsigned)qpos) ? wp[r] + (delta <= 128 ? 1.f : 0.f) : 0.f;
;         else if (RANGE == 2) w = (delta <= qpos) ? wp[r] + (delta <= 512 ? 1.f : 0.f) : 0.f;
;         else w = (delta <= lim3) ? wp[r] : 0.f;
;         const float p = w * __builtin_amdgcn_exp2f(s[r]); ps += p; s[r] = p; }
;     lsum += ps;
;     v4u pa, pb; pa.x = pk2(s[0], s[1]); pa.y = pk2(s[2], s[3]); pa.z = pk2(s[4], s[5]); pa.w = pk2(s[6], s[7]); pb.x = pk2(s[8], s[9]); pb.y = pk2(s[10], s[11]); pb.z = pk2(s[12], s[13]); pb.w = pk2(s[14], s[15]);
;     pf0 = __builtin_bit_cast(bf16x8, pa); pf1 = __builtin_bit_cast(bf16x8, pb);
.LBB0_697:
	s_andn2_b64 vcc, exec, s[2:3]
	s_cbranch_vccnz .LBB0_699
	s_and_b64 s[2:3], s[34:35], exec
	s_cselect_b32 s34, 0xffffff80, s91
	s_cselect_b32 s35, 0x500, s0
	s_and_b64 s[2:3], s[12:13], exec
	s_cselect_b32 s2, 0xffffff00, s34
	s_cselect_b32 s3, 0x800, s35
	s_mul_i32 s2, s2, s73
	s_add_i32 s2, s2, s3
	v_add_u32_e32 v2, s2, v218
	v_sub_u32_e32 v82, v2, v230
	v_cmp_gt_i32_e32 vcc, s68, v82
	v_subrev_u32_e32 v70, 36, v82
	v_subrev_u32_e32 v71, 32, v82
	v_cndmask_b32_e64 v68, 0, 1.0, vcc
	v_add_f32_e32 v68, v68, v36
	v_cmp_le_i32_e32 vcc, v82, v198
	v_subrev_u32_e32 v72, 44, v82
	v_subrev_u32_e32 v73, 40, v82
	v_cndmask_b32_e32 v83, 0, v68, vcc
	v_sub_u32_e32 v68, v2, v229
	v_cmp_gt_i32_e32 vcc, s68, v68
	v_add_u32_e32 v74, 0xffffffbc, v82
	v_subrev_u32_e32 v75, 64, v82
	v_cndmask_b32_e64 v69, 0, 1.0, vcc
	v_add_f32_e32 v69, v69, v37
	v_cmp_le_i32_e32 vcc, v68, v198
	v_sub_u32_e32 v68, v2, v227
	v_sub_u32_e32 v2, v2, v225
	v_cndmask_b32_e32 v112, 0, v69, vcc
	v_cmp_gt_i32_e32 vcc, s68, v68
	v_add_u32_e32 v80, 0xffffffb4, v82
	v_add_u32_e32 v81, 0xffffffb8, v82
	v_cndmask_b32_e64 v69, 0, 1.0, vcc
	v_add_f32_e32 v69, v69, v38
	v_cmp_le_i32_e32 vcc, v68, v198
	v_mul_f32_e32 v114, v111, v83
	v_mul_f32_e32 v115, v110, v112
	v_cndmask_b32_e32 v113, 0, v69, vcc
	v_cmp_gt_i32_e32 vcc, s68, v2
	v_mul_f32_e32 v243, v109, v113
	s_nop 0
	v_cndmask_b32_e64 v68, 0, 1.0, vcc
	v_add_f32_e32 v68, v68, v39
	v_cmp_le_i32_e32 vcc, v2, v198
	s_nop 1
	v_cndmask_b32_e32 v2, 0, v68, vcc
	v_cmp_gt_i32_e32 vcc, s68, v70
	v_mul_f32_e32 v244, v108, v2
	s_nop 0
	v_cndmask_b32_e64 v69, 0, 1.0, vcc
	v_cmp_gt_i32_e32 vcc, s68, v71
	s_nop 1
	v_cndmask_b32_e64 v68, 0, 1.0, vcc
	v_add_f32_e32 v68, v68, v40
	v_add_f32_e32 v69, v69, v41
	v_cmp_le_i32_e32 vcc, v70, v1
	s_nop 1
	v_cndmask_b32_e32 v69, 0, v69, vcc
	v_cmp_le_i32_e32 vcc, v71, v198
	s_nop 1
	v_cndmask_b32_e32 v68, 0, v68, vcc
	v_cmp_gt_i32_e32 vcc, s68, v72
	v_mul_f32_e32 v70, v106, v68
	v_mul_f32_e32 v71, v107, v69
	s_nop 0
	v_cndmask_b32_e64 v69, 0, 1.0, vcc
	v_cmp_gt_i32_e32 vcc, s68, v73
	s_nop 1
	v_cndmask_b32_e64 v68, 0, 1.0, vcc
	v_add_f32_e32 v68, v68, v42
	v_add_f32_e32 v69, v69, v43
	v_cmp_le_i32_e32 vcc, v72, v1
	s_nop 1
	v_cndmask_b32_e32 v69, 0, v69, vcc
	v_cmp_le_i32_e32 vcc, v73, v198
	s_nop 1
	v_cndmask_b32_e32 v68, 0, v68, vcc
	v_cmp_gt_i32_e32 vcc, s68, v74
	v_mul_f32_e32 v72, v104, v68
	v_mul_f32_e32 v73, v105, v69
	s_nop 0
	v_cndmask_b32_e64 v69, 0, 1.0, vcc
	v_cmp_gt_i32_e32 vcc, s68, v75
	s_nop 1
	v_cndmask_b32_e64 v68, 0, 1.0, vcc
	v_add_f32_e32 v68, v68, v44
	v_add_f32_e32 v69, v69, v45
	v_cmp_le_i32_e32 vcc, v74, v1
	s_nop 1
	v_cndmask_b32_e32 v69, 0, v69, vcc
	v_cmp_le_i32_e32 vcc, v75, v198
	s_nop 1
	v_cndmask_b32_e32 v68, 0, v68, vcc
	v_cmp_gt_i32_e32 vcc, s68, v80
	v_mul_f32_e32 v74, v102, v68
	v_mul_f32_e32 v75, v103, v69
	s_nop 0
	v_cndmask_b32_e64 v69, 0, 1.0, vcc
	v_cmp_gt_i32_e32 vcc, s68, v81
	s_nop 1
	v_cndmask_b32_e64 v68, 0, 1.0, vcc
	v_add_f32_e32 v68, v68, v46
	v_add_f32_e32 v69, v69, v47
	v_cmp_le_i32_e32 vcc, v80, v1
	s_nop 1
	v_cndmask_b32_e32 v69, 0, v69, vcc
	v_cmp_le_i32_e32 vcc, v81, v198
	s_nop 1
	v_cndmask_b32_e32 v68, 0, v68, vcc
	v_mul_f32_e32 v80, v100, v68
	v_mul_f32_e32 v81, v101, v69
	v_add_u32_e32 v100, 0xffffff9c, v82
	v_add_u32_e32 v101, 0xffffffa0, v82
	v_cmp_gt_i32_e32 vcc, s68, v100
	s_nop 1
	v_cndmask_b32_e64 v69, 0, 1.0, vcc
	v_cmp_gt_i32_e32 vcc, s68, v101
	s_nop 1
	v_cndmask_b32_e64 v68, 0, 1.0, vcc
	v_add_f32_e32 v68, v68, v48
	v_add_f32_e32 v69, v69, v49
	v_cmp_le_i32_e32 vcc, v100, v1
	s_nop 1
	v_cndmask_b32_e32 v69, 0, v69, vcc
	v_cmp_le_i32_e32 vcc, v101, v198
	s_nop 1
	v_cndmask_b32_e32 v68, 0, v68, vcc
	v_mul_f32_e32 v78, v78, v68
	v_mul_f32_e32 v79, v79, v69
	v_fma_f32 v68, v111, v83, 0
	v_fmac_f32_e32 v68, v110, v112
	v_fmac_f32_e32 v68, v109, v113
	v_fmac_f32_e32 v68, v108, v2
	v_add_f32_e32 v2, v70, v68
	v_add_f32_e32 v2, v71, v2
	v_add_f32_e32 v2, v72, v2
	v_add_u32_e32 v83, 0xffffff94, v82
	v_add_f32_e32 v2, v73, v2
	v_add_u32_e32 v82, 0xffffff98, v82
	v_cmp_gt_i32_e32 vcc, s68, v83
	v_add_f32_e32 v2, v74, v2
	v_add_f32_e32 v2, v75, v2
	v_cndmask_b32_e64 v69, 0, 1.0, vcc
	v_cmp_gt_i32_e32 vcc, s68, v82
	v_add_f32_e32 v2, v80, v2
	v_add_f32_e32 v2, v81, v2
	v_cndmask_b32_e64 v68, 0, 1.0, vcc
	v_add_f32_e32 v68, v68, v50
	v_add_f32_e32 v69, v69, v51
	v_cmp_le_i32_e32 vcc, v83, v1
	v_add_f32_e32 v2, v78, v2
	v_add_f32_e32 v2, v79, v2
	v_cndmask_b32_e32 v69, 0, v69, vcc
	v_cmp_le_i32_e32 vcc, v82, v198
	s_nop 1
	v_cndmask_b32_e32 v68, 0, v68, vcc
	v_mul_f32_e32 v76, v76, v68
	v_mul_f32_e32 v77, v77, v69
	v_cvt_pk_bf16_f32 v68, v114, v115
	v_cvt_pk_bf16_f32 v69, v243, v244
	v_cvt_pk_bf16_f32 v70, v70, v71
	v_cvt_pk_bf16_f32 v71, v72, v73
	v_cvt_pk_bf16_f32 v72, v74, v75
	s_nop 0
	v_add_f32_e32 v2, v76, v2
	v_add_f32_e32 v2, v77, v2
	v_cvt_pk_bf16_f32 v73, v80, v81
	v_cvt_pk_bf16_f32 v74, v78, v79
	v_cvt_pk_bf16_f32 v75, v76, v77

; __device__ __forceinline__ unsigned pk2(float lo, float hi) { return pg8::cvt_pk_bf16(lo, hi); }
; template <int RANGE>
; __device__ __forceinline__ void a_softmax(f32x16 s, int tt, int P0, int qpos, int lane, const float (&wp)[16], bf16x8& pf0, bf16x8& pf1, float& lsum) {
;     constexpr int ST = RANGE == 3 ? 8 : (RANGE == 2 ? 4 : 1);
;     int kbase, stride; a_tile_desc(tt, P0, kbase, stride);
;     const int hi = lane >> 5;
;     const int d0 = qpos - kbase - ST * 4 * hi;
;     const int lim3 = qpos < 2048 ? qpos : 2048;
;     float ps = 0.f;
; #pragma unroll
;     for (int r = 0; r < 16; ++r) { const int delta = d0 - ST * ((r & 3) + 8 * (r >> 2)); float w;
;         if (RANGE == 1) w = ((unsigned)delta <= (unsigned)qpos) ? wp[r] + (delta <= 128 ? 1.f : 0.f) : 0.f;
;         else if (RANGE == 2) w = (delta <= qpos) ? wp[r] + (delta <= 512 ? 1.f : 0.f) : 0.f;
;         else w = (delta <= lim3) ? wp[r] : 0.f;
;         const float p = w * __builtin_amdgcn_exp2f(s[r]); ps += p; s[r] = p; }
;     lsum += ps;
;     v4u pa, pb; pa.x = pk2(s[0], s[1]); pa.y = pk2(s[2], s[3]); pa.z = pk2(s[4], s[5]); pa.w = pk2(s[6], s[7]); pb.x = pk2(s[8], s[9]); pb.y = pk2(s[10], s[11]); pb.z = pk2(s[12], s[13]); pb.w = pk2(s[14], s[15]);
;     pf0 = __builtin_bit_cast(bf16x8, pa); pf1 = __builtin_bit_cast(bf16x8, pb);
; }
.LBB0_706:
	v_exp_f32_e32 v111, v84
	v_exp_f32_e32 v110, v85
	v_exp_f32_e32 v109, v86
	v_exp_f32_e32 v108, v87
	v_exp_f32_e32 v106, v88
	v_exp_f32_e32 v107, v89
	v_exp_f32_e32 v104, v90
	v_exp_f32_e32 v105, v91
	v_exp_f32_e32 v102, v92
	v_exp_f32_e32 v103, v93
	v_exp_f32_e32 v100, v94
	v_exp_f32_e32 v101, v95
	v_exp_f32_e32 v94, v96
	v_exp_f32_e32 v95, v97
	v_exp_f32_e32 v92, v98
	v_exp_f32_e32 v93, v99
	s_cmp_lt_u32 s80, 9
	s_cselect_b64 s[34:35], -1, 0
	s_cmp_gt_i32 s37, 2
	s_mov_b64 s[2:3], -1
	s_cbranch_scc0 .LBB0_708
	s_and_b64 s[2:3], s[34:35], exec
	s_cselect_b32 s38, 0xffffff80, s91
	s_cselect_b32 s39, 0x500, s0
	s_and_b64 s[2:3], s[12:13], exec
	s_cselect_b32 s2, 0xffffff00, s38
	s_cselect_b32 s3, 0x800, s39
	s_mul_i32 s2, s2, s80
	s_add_i32 s2, s2, s3
	v_add_u32_e32 v90, s2, v237
	v_cmp_le_i32_e32 vcc, v90, v198
	v_add_u32_e32 v84, -8, v90
	v_add_u32_e32 v85, 0xffffffb8, v90
	v_cndmask_b32_e32 v91, 0, v36, vcc
	v_cmp_le_i32_e32 vcc, v84, v198
	v_add_u32_e32 v84, -16, v90
	v_add_u32_e32 v87, 0xffffffa8, v90
	v_cndmask_b32_e32 v96, 0, v37, vcc
	v_cmp_le_i32_e32 vcc, v84, v198
	v_subrev_u32_e32 v84, 24, v90
	v_add_u32_e32 v86, 0xffffffb0, v90
	v_cndmask_b32_e32 v97, 0, v38, vcc
	v_cmp_le_i32_e32 vcc, v84, v198
	v_subrev_u32_e32 v84, 64, v90
	v_add_u32_e32 v89, 0xffffff78, v90
	v_cndmask_b32_e32 v243, 0, v39, vcc
	v_cmp_le_i32_e32 vcc, v85, v1
	v_add_u32_e32 v88, 0xffffff80, v90
	v_mul_f32_e32 v246, v111, v91
	v_cndmask_b32_e32 v85, 0, v41, vcc
	v_cmp_le_i32_e32 vcc, v84, v198
	v_mul_f32_e32 v247, v110, v96
	v_mul_f32_e32 v248, v109, v97
	v_cndmask_b32_e32 v84, 0, v40, vcc
	v_cmp_le_i32_e32 vcc, v87, v1
	v_mul_f32_e32 v84, v106, v84
	v_mul_f32_e32 v85, v107, v85
	v_mul_f32_e32 v249, v108, v243
	v_cndmask_b32_e32 v87, 0, v43, vcc
	v_cmp_le_i32_e32 vcc, v86, v198
	s_mov_b64 s[2:3], 0
	s_nop 0
	v_cndmask_b32_e32 v86, 0, v42, vcc
	v_cmp_le_i32_e32 vcc, v89, v1
	v_mul_f32_e32 v86, v104, v86
	v_mul_f32_e32 v87, v105, v87
	s_nop 0
	v_cndmask_b32_e32 v89, 0, v45, vcc
	v_cmp_le_i32_e32 vcc, v88, v198
	s_nop 1
	v_cndmask_b32_e32 v88, 0, v44, vcc
	v_mul_f32_e32 v98, v102, v88
	v_mul_f32_e32 v99, v103, v89
	v_add_u32_e32 v89, 0xffffff68, v90
	v_add_u32_e32 v88, 0xffffff70, v90
	v_cmp_le_i32_e32 vcc, v89, v1
	s_nop 1
	v_cndmask_b32_e32 v89, 0, v47, vcc
	v_cmp_le_i32_e32 vcc, v88, v198
	s_nop 1
	v_cndmask_b32_e32 v88, 0, v46, vcc
	v_mul_f32_e32 v112, v100, v88
	v_mul_f32_e32 v113, v101, v89
	v_add_u32_e32 v89, 0xffffff38, v90
	v_add_u32_e32 v88, 0xffffff40, v90
	v_cmp_le_i32_e32 vcc, v89, v1
	s_nop 1
	v_cndmask_b32_e32 v89, 0, v49, vcc
	v_cmp_le_i32_e32 vcc, v88, v198
	s_nop 1
	v_cndmask_b32_e32 v88, 0, v48, vcc
	v_mul_f32_e32 v114, v94, v88
	v_mul_f32_e32 v115, v95, v89
	v_fma_f32 v88, v111, v91, 0
	v_fmac_f32_e32 v88, v110, v96
	v_fmac_f32_e32 v88, v109, v97
	v_fmac_f32_e32 v88, v108, v243
	v_add_f32_e32 v88, v84, v88
	v_add_f32_e32 v88, v85, v88
	v_add_f32_e32 v88, v86, v88
	v_add_f32_e32 v88, v87, v88
	v_add_f32_e32 v88, v98, v88
	v_add_f32_e32 v88, v99, v88
	v_add_f32_e32 v88, v112, v88
	v_add_f32_e32 v88, v113, v88
	v_add_f32_e32 v88, v114, v88
	v_add_u32_e32 v89, 0xffffff28, v90
	v_add_f32_e32 v91, v115, v88
	v_add_u32_e32 v88, 0xffffff30, v90
	v_cmp_le_i32_e32 vcc, v89, v1
	s_nop 1
	v_cndmask_b32_e32 v89, 0, v51, vcc
	v_cmp_le_i32_e32 vcc, v88, v198
	s_nop 1
	v_cndmask_b32_e32 v88, 0, v50, vcc
	v_mul_f32_e32 v244, v92, v88
	v_mul_f32_e32 v245, v93, v89
	s_nop 0
	v_add_f32_e32 v88, v244, v91
	v_add_f32_e32 v96, v245, v88
	v_cvt_pk_bf16_f32 v88, v246, v247
	v_cvt_pk_bf16_f32 v89, v248, v249
	v_cvt_pk_bf16_f32 v90, v84, v85
	v_cvt_pk_bf16_f32 v91, v86, v87
	v_cvt_pk_bf16_f32 v84, v98, v99
	v_cvt_pk_bf16_f32 v85, v112, v113
	v_cvt_pk_bf16_f32 v86, v114, v115
	v_cvt_pk_bf16_f32 v87, v244, v245
.LBB0_708:
	s_andn2_b64 vcc, exec, s[2:3]
	s_cbranch_vccnz .LBB0_713
	s_cmp_lg_u32 s37, 2
	s_mov_b64 s[2:3], -1
	s_cbranch_scc0 .LBB0_711
	s_and_b64 s[2:3], s[34:35], exec
	s_cselect_b32 s37, 7, 5
	s_cselect_b32 s38, s77, s76
	s_and_b64 s[2:3], s[12:13], exec
	s_cselect_b32 s2, 8, s37
	s_cselect_b32 s3, s72, s38
	s_lshl_b32 s2, s80, s2
	s_add_i32 s2, s2, s3
	v_add_u32_e32 v90, s2, v232
	v_sub_co_u32_e32 v84, vcc, v198, v90
	v_cmp_gt_u32_e64 s[2:3], s1, v84
	v_add_u32_e32 v87, 9, v90
	v_add_u32_e32 v86, 8, v90
	v_cndmask_b32_e64 v84, 0, 1.0, s[2:3]
	v_add_f32_e32 v84, v84, v36
	v_cndmask_b32_e64 v91, v84, 0, vcc
	v_add_u32_e32 v84, 1, v90
	v_sub_co_u32_e32 v84, vcc, v198, v84
	v_cmp_gt_u32_e64 s[2:3], s1, v84
	v_sub_u32_e32 v88, v198, v86
	v_add_u32_e32 v89, 11, v90
	v_cndmask_b32_e64 v84, 0, 1.0, s[2:3]
	v_add_f32_e32 v84, v84, v37
	v_cndmask_b32_e64 v96, v84, 0, vcc
	v_add_u32_e32 v84, 2, v90
	v_sub_co_u32_e32 v84, vcc, v198, v84
	v_cmp_gt_u32_e64 s[2:3], s1, v84
	v_add_u32_e32 v99, 17, v90
	v_add_u32_e32 v113, 19, v90
	v_cndmask_b32_e64 v84, 0, 1.0, s[2:3]
	v_add_f32_e32 v84, v84, v38
	v_cndmask_b32_e64 v97, v84, 0, vcc
	v_add_u32_e32 v84, 3, v90
	v_sub_co_u32_e32 v84, vcc, v198, v84
	v_cmp_gt_u32_e64 s[2:3], s1, v84
	v_add_u32_e32 v115, 25, v90
	v_mul_f32_e32 v247, v110, v96
	v_cndmask_b32_e64 v84, 0, 1.0, s[2:3]
	v_add_f32_e32 v84, v84, v39
	v_cndmask_b32_e64 v243, v84, 0, vcc
	v_sub_u32_e32 v84, v1, v87
	v_cmp_gt_u32_e32 vcc, s1, v84
	v_mul_f32_e32 v246, v111, v91
	v_mul_f32_e32 v248, v109, v97
	v_cndmask_b32_e64 v85, 0, 1.0, vcc
	v_cmp_gt_u32_e32 vcc, s1, v88
	v_add_u32_e32 v88, 10, v90
	v_sub_u32_e32 v98, v198, v88
	v_cndmask_b32_e64 v84, 0, 1.0, vcc
	v_add_f32_e32 v84, v84, v40
	v_add_f32_e32 v85, v85, v41
	v_cmp_ge_u32_e32 vcc, v1, v87
	v_mul_f32_e32 v249, v108, v243
	s_mov_b64 s[2:3], 0
	v_cndmask_b32_e32 v85, 0, v85, vcc
	v_cmp_ge_u32_e32 vcc, v198, v86
; __device__ __forceinline__ unsigned pk2(float lo, float hi) { return pg8::cvt_pk_bf16(lo, hi); }
; template <int RANGE>
; __device__ __forceinline__ void a_softmax(f32x16 s, int tt, int P0, int qpos, int lane, const float (&wp)[16], bf16x8& pf0, bf16x8& pf1, float& lsum) {
;     ...
;     for (int r = 0; r < 16; ++r) { const int delta = d0 - ST * ((r & 3) + 8 * (r >> 2)); float w;
;         if (RANGE == 1) w = ((unsigned)delta <= (unsigned)qpos) ? wp[r] + (delta <= 128 ? 1.f : 0.f) : 0.f;
;         else if (RANGE == 2) w = (delta <= qpos) ? wp[r] + (delta <= 512 ? 1.f : 0.f) : 0.f;
;         else w = (delta <= lim3) ? wp[r] : 0.f;
;         const float p = w * __builtin_amdgcn_exp2f(s[r]); ps += p; s[r] = p; }
;     lsum += ps;
;     v4u pa, pb; pa.x = pk2(s[0], s[1]); pa.y = pk2(s[2], s[3]); pa.z = pk2(s[4], s[5]); pa.w = pk2(s[6], s[7]); pb.x = pk2(s[8], s[9]); pb.y = pk2(s[10], s[11]); pb.z = pk2(s[12], s[13]); pb.w = pk2(s[14], s[15]);
;     pf0 = __builtin_bit_cast(bf16x8, pa); pf1 = __builtin_bit_cast(bf16x8, pb);
	v_sub_u32_e32 v86, v1, v89
	s_nop 0
	v_cndmask_b32_e32 v84, 0, v84, vcc
	v_cmp_gt_u32_e32 vcc, s1, v86
	v_mul_f32_e32 v84, v106, v84
	v_mul_f32_e32 v85, v107, v85
	s_nop 0
	v_cndmask_b32_e64 v87, 0, 1.0, vcc
	v_cmp_gt_u32_e32 vcc, s1, v98
	v_add_u32_e32 v98, 16, v90
	v_sub_u32_e32 v112, v198, v98
	v_cndmask_b32_e64 v86, 0, 1.0, vcc
	v_add_f32_e32 v86, v86, v42
	v_add_f32_e32 v87, v87, v43
	v_cmp_ge_u32_e32 vcc, v1, v89
	s_nop 1
	v_cndmask_b32_e32 v87, 0, v87, vcc
	v_cmp_ge_u32_e32 vcc, v198, v88
	v_sub_u32_e32 v88, v1, v99
	s_nop 0
	v_cndmask_b32_e32 v86, 0, v86, vcc
	v_cmp_gt_u32_e32 vcc, s1, v88
	v_mul_f32_e32 v86, v104, v86
	v_mul_f32_e32 v87, v105, v87
	s_nop 0
	v_cndmask_b32_e64 v89, 0, 1.0, vcc
	v_cmp_gt_u32_e32 vcc, s1, v112
	v_add_u32_e32 v112, 18, v90
	v_sub_u32_e32 v114, v198, v112
	v_cndmask_b32_e64 v88, 0, 1.0, vcc
	v_add_f32_e32 v88, v88, v44
	v_add_f32_e32 v89, v89, v45
	v_cmp_ge_u32_e32 vcc, v1, v99
	s_nop 1
	v_cndmask_b32_e32 v89, 0, v89, vcc
	v_cmp_ge_u32_e32 vcc, v198, v98
	s_nop 1
	v_cndmask_b32_e32 v88, 0, v88, vcc
	v_mul_f32_e32 v98, v102, v88
	v_mul_f32_e32 v99, v103, v89
	v_sub_u32_e32 v88, v1, v113
	v_cmp_gt_u32_e32 vcc, s1, v88
	s_nop 1
	v_cndmask_b32_e64 v89, 0, 1.0, vcc
	v_cmp_gt_u32_e32 vcc, s1, v114
	v_add_u32_e32 v114, 24, v90
	v_sub_u32_e32 v244, v198, v114
	v_cndmask_b32_e64 v88, 0, 1.0, vcc
	v_add_f32_e32 v88, v88, v46
	v_add_f32_e32 v89, v89, v47
	v_cmp_ge_u32_e32 vcc, v1, v113
	s_nop 1
	v_cndmask_b32_e32 v89, 0, v89, vcc
	v_cmp_ge_u32_e32 vcc, v198, v112
	s_nop 1
	v_cndmask_b32_e32 v88, 0, v88, vcc
	v_mul_f32_e32 v112, v100, v88
	v_mul_f32_e32 v113, v101, v89
	v_sub_u32_e32 v88, v1, v115
	v_cmp_gt_u32_e32 vcc, s1, v88
	s_nop 1
	v_cndmask_b32_e64 v89, 0, 1.0, vcc
	v_cmp_gt_u32_e32 vcc, s1, v244
	s_nop 1
	v_cndmask_b32_e64 v88, 0, 1.0, vcc
	v_add_f32_e32 v88, v88, v48
	v_add_f32_e32 v89, v89, v49
	v_cmp_ge_u32_e32 vcc, v1, v115
	s_nop 1
	v_cndmask_b32_e32 v89, 0, v89, vcc
	v_cmp_ge_u32_e32 vcc, v198, v114
	s_nop 1
	v_cndmask_b32_e32 v88, 0, v88, vcc
	v_mul_f32_e32 v114, v94, v88
	v_mul_f32_e32 v115, v95, v89
	v_fma_f32 v88, v111, v91, 0
	v_fmac_f32_e32 v88, v110, v96
	v_fmac_f32_e32 v88, v109, v97
	v_fmac_f32_e32 v88, v108, v243
	v_add_f32_e32 v88, v84, v88
	v_add_f32_e32 v88, v85, v88
	v_add_f32_e32 v88, v86, v88
	v_add_f32_e32 v88, v87, v88
	v_add_f32_e32 v88, v98, v88
	v_add_f32_e32 v88, v99, v88
	v_add_f32_e32 v88, v112, v88
	v_add_f32_e32 v88, v113, v88
	v_add_f32_e32 v88, v114, v88
	v_add_u32_e32 v96, 26, v90
	v_add_u32_e32 v90, 27, v90
	v_add_f32_e32 v91, v115, v88
	v_sub_u32_e32 v88, v1, v90
	v_sub_u32_e32 v97, v198, v96
	v_cmp_gt_u32_e32 vcc, s1, v88
	s_nop 1
	v_cndmask_b32_e64 v89, 0, 1.0, vcc
	v_cmp_gt_u32_e32 vcc, s1, v97
	s_nop 1
	v_cndmask_b32_e64 v88, 0, 1.0, vcc
	v_add_f32_e32 v88, v88, v50
	v_add_f32_e32 v89, v89, v51
	v_cmp_ge_u32_e32 vcc, v1, v90
	s_nop 1
	v_cndmask_b32_e32 v89, 0, v89, vcc
	v_cmp_ge_u32_e32 vcc, v198, v96
	s_nop 1
	v_cndmask_b32_e32 v88, 0, v88, vcc
	v_mul_f32_e32 v244, v92, v88
	v_mul_f32_e32 v245, v93, v89
	s_nop 0
	v_add_f32_e32 v88, v244, v91
	v_add_f32_e32 v96, v245, v88
	v_cvt_pk_bf16_f32 v88, v246, v247
	v_cvt_pk_bf16_f32 v89, v248, v249
	v_cvt_pk_bf16_f32 v90, v84, v85
	v_cvt_pk_bf16_f32 v91, v86, v87
	v_cvt_pk_bf16_f32 v84, v98, v99
	v_cvt_pk_bf16_f32 v85, v112, v113
	v_cvt_pk_bf16_f32 v86, v114, v115
	v_cvt_pk_bf16_f32 v87, v244, v245
; __device__ __forceinline__ unsigned pk2(float lo, float hi) { return pg8::cvt_pk_bf16(lo, hi); }
; template <int RANGE>
; __device__ __forceinline__ void a_softmax(f32x16 s, int tt, int P0, int qpos, int lane, const float (&wp)[16], bf16x8& pf0, bf16x8& pf1, float& lsum) {
;     ...
;     for (int r = 0; r < 16; ++r) { const int delta = d0 - ST * ((r & 3) + 8 * (r >> 2)); float w;
;         if (RANGE == 1) w = ((unsigned)delta <= (unsigned)qpos) ? wp[r] + (delta <= 128 ? 1.f : 0.f) : 0.f;
;         else if (RANGE == 2) w = (delta <= qpos) ? wp[r] + (delta <= 512 ? 1.f : 0.f) : 0.f;
;         else w = (delta <= lim3) ? wp[r] : 0.f;
;         const float p = w * __builtin_amdgcn_exp2f(s[r]); ps += p; s[r] = p; }
;     lsum += ps;
;     v4u pa, pb; pa.x = pk2(s[0], s[1]); pa.y = pk2(s[2], s[3]); pa.z = pk2(s[4], s[5]); pa.w = pk2(s[6], s[7]); pb.x = pk2(s[8], s[9]); pb.y = pk2(s[10], s[11]); pb.z = pk2(s[12], s[13]); pb.w = pk2(s[14], s[15]);
;     pf0 = __builtin_bit_cast(bf16x8, pa); pf1 = __builtin_bit_cast(bf16x8, pb);
.LBB0_711:
	s_andn2_b64 vcc, exec, s[2:3]
	s_cbranch_vccnz .LBB0_713
	s_and_b64 s[2:3], s[34:35], exec
	s_cselect_b32 s34, 0xffffff80, s91
	s_cselect_b32 s35, 0x500, s0
	s_and_b64 s[2:3], s[12:13], exec
	s_cselect_b32 s2, 0xffffff00, s34
	s_cselect_b32 s3, 0x800, s35
	s_mul_i32 s2, s2, s80
	s_add_i32 s2, s2, s3
	v_add_u32_e32 v84, s2, v218
	v_sub_u32_e32 v90, v84, v230
	v_cmp_gt_i32_e32 vcc, s68, v90
	v_subrev_u32_e32 v87, 32, v90
	v_subrev_u32_e32 v88, 44, v90
	v_cndmask_b32_e64 v85, 0, 1.0, vcc
	v_add_f32_e32 v85, v85, v36
	v_cmp_le_i32_e32 vcc, v90, v198
	v_subrev_u32_e32 v89, 40, v90
	v_add_u32_e32 v98, 0xffffffbc, v90
	v_cndmask_b32_e32 v91, 0, v85, vcc
	v_sub_u32_e32 v85, v84, v229
	v_cmp_gt_i32_e32 vcc, s68, v85
	v_subrev_u32_e32 v99, 64, v90
	v_mul_f32_e32 v113, v111, v91
	v_cndmask_b32_e64 v86, 0, 1.0, vcc
	v_add_f32_e32 v86, v86, v37
	v_cmp_le_i32_e32 vcc, v85, v198
	v_sub_u32_e32 v85, v84, v227
	v_sub_u32_e32 v84, v84, v225
	v_cndmask_b32_e32 v96, 0, v86, vcc
	v_cmp_gt_i32_e32 vcc, s68, v85
	v_mul_f32_e32 v114, v110, v96
	s_nop 0
	v_cndmask_b32_e64 v86, 0, 1.0, vcc
	v_add_f32_e32 v86, v86, v38
	v_cmp_le_i32_e32 vcc, v85, v198
	s_nop 1
	v_cndmask_b32_e32 v97, 0, v86, vcc
	v_cmp_gt_i32_e32 vcc, s68, v84
	v_subrev_u32_e32 v86, 36, v90
	v_mul_f32_e32 v115, v109, v97
	v_cndmask_b32_e64 v85, 0, 1.0, vcc
	v_add_f32_e32 v85, v85, v39
	v_cmp_le_i32_e32 vcc, v84, v198
	s_nop 1
	v_cndmask_b32_e32 v112, 0, v85, vcc
	v_cmp_gt_i32_e32 vcc, s68, v86
	v_mul_f32_e32 v243, v108, v112
	s_nop 0
	v_cndmask_b32_e64 v85, 0, 1.0, vcc
	v_cmp_gt_i32_e32 vcc, s68, v87
	s_nop 1
	v_cndmask_b32_e64 v84, 0, 1.0, vcc
	v_add_f32_e32 v84, v84, v40
	v_add_f32_e32 v85, v85, v41
	v_cmp_le_i32_e32 vcc, v86, v1
	s_nop 1
	v_cndmask_b32_e32 v85, 0, v85, vcc
	v_cmp_le_i32_e32 vcc, v87, v198
	s_nop 1
	v_cndmask_b32_e32 v84, 0, v84, vcc
	v_cmp_gt_i32_e32 vcc, s68, v88
	v_mul_f32_e32 v84, v106, v84
	v_mul_f32_e32 v85, v107, v85
	s_nop 0
	v_cndmask_b32_e64 v87, 0, 1.0, vcc
	v_cmp_gt_i32_e32 vcc, s68, v89
	s_nop 1
	v_cndmask_b32_e64 v86, 0, 1.0, vcc
	v_add_f32_e32 v86, v86, v42
	v_add_f32_e32 v87, v87, v43
	v_cmp_le_i32_e32 vcc, v88, v1
	s_nop 1
	v_cndmask_b32_e32 v87, 0, v87, vcc
	v_cmp_le_i32_e32 vcc, v89, v198
	s_nop 1
	v_cndmask_b32_e32 v86, 0, v86, vcc
	v_cmp_gt_i32_e32 vcc, s68, v98
	v_mul_f32_e32 v86, v104, v86
	v_mul_f32_e32 v87, v105, v87
	s_nop 0
	v_cndmask_b32_e64 v89, 0, 1.0, vcc
	v_cmp_gt_i32_e32 vcc, s68, v99
	s_nop 1
	v_cndmask_b32_e64 v88, 0, 1.0, vcc
	v_add_f32_e32 v88, v88, v44
	v_add_f32_e32 v89, v89, v45
	v_cmp_le_i32_e32 vcc, v98, v1
	s_nop 1
	v_cndmask_b32_e32 v89, 0, v89, vcc
	v_cmp_le_i32_e32 vcc, v99, v198
	s_nop 1
	v_cndmask_b32_e32 v88, 0, v88, vcc
	v_mul_f32_e32 v98, v102, v88
	v_mul_f32_e32 v99, v103, v89
	v_add_u32_e32 v102, 0xffffffb4, v90
	v_add_u32_e32 v103, 0xffffffb8, v90
	v_cmp_gt_i32_e32 vcc, s68, v102
	s_nop 1
	v_cndmask_b32_e64 v89, 0, 1.0, vcc
	v_cmp_gt_i32_e32 vcc, s68, v103
	s_nop 1
	v_cndmask_b32_e64 v88, 0, 1.0, vcc
	v_add_f32_e32 v88, v88, v46
	v_add_f32_e32 v89, v89, v47
	v_cmp_le_i32_e32 vcc, v102, v1
	v_add_u32_e32 v102, 0xffffff9c, v90
	s_nop 0
	v_cndmask_b32_e32 v89, 0, v89, vcc
	v_cmp_le_i32_e32 vcc, v103, v198
	v_add_u32_e32 v103, 0xffffffa0, v90
	s_nop 0
	v_cndmask_b32_e32 v88, 0, v88, vcc
	v_cmp_gt_i32_e32 vcc, s68, v102
	v_mul_f32_e32 v100, v100, v88
	v_mul_f32_e32 v101, v101, v89
	s_nop 0
	v_cndmask_b32_e64 v89, 0, 1.0, vcc
	v_cmp_gt_i32_e32 vcc, s68, v103
	s_nop 1
	v_cndmask_b32_e64 v88, 0, 1.0, vcc
	v_add_f32_e32 v88, v88, v48
	v_add_f32_e32 v89, v89, v49
	v_cmp_le_i32_e32 vcc, v102, v1
	s_nop 1
	v_cndmask_b32_e32 v89, 0, v89, vcc
	v_cmp_le_i32_e32 vcc, v103, v198
	s_nop 1
	v_cndmask_b32_e32 v88, 0, v88, vcc
	v_mul_f32_e32 v94, v94, v88
	v_mul_f32_e32 v95, v95, v89
	v_fma_f32 v88, v111, v91, 0
	v_fmac_f32_e32 v88, v110, v96
	v_fmac_f32_e32 v88, v109, v97
	v_fmac_f32_e32 v88, v108, v112
	v_add_f32_e32 v88, v84, v88
	v_add_f32_e32 v88, v85, v88
	v_add_f32_e32 v88, v86, v88
	v_add_f32_e32 v88, v87, v88
	v_add_f32_e32 v88, v98, v88
	v_add_f32_e32 v88, v99, v88
	v_add_f32_e32 v88, v100, v88
	v_add_u32_e32 v96, 0xffffff94, v90
	v_add_f32_e32 v88, v101, v88
	v_add_u32_e32 v90, 0xffffff98, v90
	v_cmp_gt_i32_e32 vcc, s68, v96
	v_add_f32_e32 v88, v94, v88
	v_add_f32_e32 v91, v95, v88
	v_cndmask_b32_e64 v89, 0, 1.0, vcc
	v_cmp_gt_i32_e32 vcc, s68, v90
	s_nop 1
	v_cndmask_b32_e64 v88, 0, 1.0, vcc
	v_add_f32_e32 v88, v88, v50
	v_add_f32_e32 v89, v89, v51
	v_cmp_le_i32_e32 vcc, v96, v1
	s_nop 1
	v_cndmask_b32_e32 v89, 0, v89, vcc
	v_cmp_le_i32_e32 vcc, v90, v198
	s_nop 1
	v_cndmask_b32_e32 v88, 0, v88, vcc
	v_mul_f32_e32 v92, v92, v88
	v_mul_f32_e32 v93, v93, v89
	s_nop 0
	v_add_f32_e32 v88, v92, v91
	v_add_f32_e32 v96, v93, v88
	v_cvt_pk_bf16_f32 v88, v113, v114
	v_cvt_pk_bf16_f32 v89, v115, v243
	v_cvt_pk_bf16_f32 v90, v84, v85
	v_cvt_pk_bf16_f32 v91, v86, v87
	v_cvt_pk_bf16_f32 v84, v98, v99
	v_cvt_pk_bf16_f32 v85, v100, v101
	v_cvt_pk_bf16_f32 v86, v94, v95
	v_cvt_pk_bf16_f32 v87, v92, v93

; __device__ __forceinline__ unsigned pk2(float lo, float hi) { return pg8::cvt_pk_bf16(lo, hi); }
; template <int RANGE>
; __device__ __forceinline__ void a_softmax(f32x16 s, int tt, int P0, int qpos, int lane, const float (&wp)[16], bf16x8& pf0, bf16x8& pf1, float& lsum) {
;     constexpr int ST = RANGE == 3 ? 8 : (RANGE == 2 ? 4 : 1);
;     int kbase, stride; a_tile_desc(tt, P0, kbase, stride);
;     const int hi = lane >> 5;
;     const int d0 = qpos - kbase - ST * 4 * hi;
;     const int lim3 = qpos < 2048 ? qpos : 2048;
;     float ps = 0.f;
; #pragma unroll
;     for (int r = 0; r < 16; ++r) { const int delta = d0 - ST * ((r & 3) + 8 * (r >> 2)); float w;
;         if (RANGE == 1) w = ((unsigned)delta <= (unsigned)qpos) ? wp[r] + (delta <= 128 ? 1.f : 0.f) : 0.f;
;         else if (RANGE == 2) w = (delta <= qpos) ? wp[r] + (delta <= 512 ? 1.f : 0.f) : 0.f;
;         else w = (delta <= lim3) ? wp[r] : 0.f;
;         const float p = w * __builtin_amdgcn_exp2f(s[r]); ps += p; s[r] = p; }
;     lsum += ps;
;     v4u pa, pb; pa.x = pk2(s[0], s[1]); pa.y = pk2(s[2], s[3]); pa.z = pk2(s[4], s[5]); pa.w = pk2(s[6], s[7]); pb.x = pk2(s[8], s[9]); pb.y = pk2(s[10], s[11]); pb.z = pk2(s[12], s[13]); pb.w = pk2(s[14], s[15]);
;     pf0 = __builtin_bit_cast(bf16x8, pa); pf1 = __builtin_bit_cast(bf16x8, pb);
; }
.LBB0_727:
	v_exp_f32_e32 v86, v68
	v_exp_f32_e32 v85, v69
	v_exp_f32_e32 v84, v70
	v_exp_f32_e32 v2, v71
	v_exp_f32_e32 v70, v72
	v_exp_f32_e32 v71, v73
	v_exp_f32_e32 v68, v74
	v_exp_f32_e32 v69, v75
	v_exp_f32_e32 v66, v76
	v_exp_f32_e32 v67, v77
	v_exp_f32_e32 v64, v78
	v_exp_f32_e32 v65, v79
	v_exp_f32_e32 v62, v80
	v_exp_f32_e32 v63, v81
	v_exp_f32_e32 v60, v82
	v_exp_f32_e32 v61, v83
	v_readlane_b32 s92, v251, 51
	v_readlane_b32 s84, v251, 53
	s_cmp_lt_u32 s40, 9
	v_readlane_b32 s93, v251, 52
	v_readlane_b32 s85, v251, 54
	s_cselect_b64 s[6:7], -1, 0
	s_cmp_gt_i32 s12, 2
	s_mov_b64 s[2:3], -1
	s_cbranch_scc0 .LBB0_729
	s_and_b64 s[2:3], s[6:7], exec
	s_cselect_b32 s13, 0xffffff80, s91
	s_cselect_b32 s34, 0x500, s0
	s_and_b64 s[2:3], s[4:5], exec
	s_cselect_b32 s2, 0xffffff00, s13
	s_cselect_b32 s3, 0x800, s34
	s_mul_i32 s2, s2, s40
	s_add_i32 s2, s2, s3
	v_add_u32_e32 v72, s2, v237
	v_cmp_le_i32_e32 vcc, v72, v198
	v_add_u32_e32 v52, -8, v72
	v_add_u32_e32 v53, 0xffffffb8, v72
	v_cndmask_b32_e32 v73, 0, v36, vcc
	v_cmp_le_i32_e32 vcc, v52, v198
	v_add_u32_e32 v52, -16, v72
	v_mul_f32_e32 v81, v86, v73
	v_cndmask_b32_e32 v78, 0, v37, vcc
	v_cmp_le_i32_e32 vcc, v52, v198
	v_subrev_u32_e32 v52, 24, v72
	v_mul_f32_e32 v82, v85, v78
	v_cndmask_b32_e32 v79, 0, v38, vcc
	v_cmp_le_i32_e32 vcc, v52, v198
	v_subrev_u32_e32 v52, 64, v72
	v_mul_f32_e32 v83, v84, v79
	v_cndmask_b32_e32 v80, 0, v39, vcc
	v_cmp_le_i32_e32 vcc, v53, v1
	v_mul_f32_e32 v87, v2, v80
	s_mov_b64 s[2:3], 0
	v_cndmask_b32_e32 v53, 0, v41, vcc
	v_cmp_le_i32_e32 vcc, v52, v198
	s_nop 1
	v_cndmask_b32_e32 v52, 0, v40, vcc
	v_mul_f32_e32 v54, v70, v52
	v_mul_f32_e32 v55, v71, v53
	v_add_u32_e32 v53, 0xffffffa8, v72
	v_add_u32_e32 v52, 0xffffffb0, v72
	v_cmp_le_i32_e32 vcc, v53, v1
	s_nop 1
	v_cndmask_b32_e32 v53, 0, v43, vcc
	v_cmp_le_i32_e32 vcc, v52, v198
	s_nop 1
	v_cndmask_b32_e32 v52, 0, v42, vcc
	v_mul_f32_e32 v56, v68, v52
	v_mul_f32_e32 v57, v69, v53
	v_add_u32_e32 v53, 0xffffff78, v72
	v_add_u32_e32 v52, 0xffffff80, v72
	v_cmp_le_i32_e32 vcc, v53, v1
	s_nop 1
	v_cndmask_b32_e32 v53, 0, v45, vcc
	v_cmp_le_i32_e32 vcc, v52, v198
	s_nop 1
	v_cndmask_b32_e32 v52, 0, v44, vcc
	v_mul_f32_e32 v58, v66, v52
	v_mul_f32_e32 v59, v67, v53
	v_add_u32_e32 v53, 0xffffff68, v72
	v_add_u32_e32 v52, 0xffffff70, v72
	v_cmp_le_i32_e32 vcc, v53, v1
	s_nop 1
	v_cndmask_b32_e32 v53, 0, v47, vcc
	v_cmp_le_i32_e32 vcc, v52, v198
	s_nop 1
	v_cndmask_b32_e32 v52, 0, v46, vcc
	v_mul_f32_e32 v74, v64, v52
	v_mul_f32_e32 v75, v65, v53
	v_add_u32_e32 v53, 0xffffff38, v72
	v_add_u32_e32 v52, 0xffffff40, v72
	v_cmp_le_i32_e32 vcc, v53, v1
	s_nop 1
	v_cndmask_b32_e32 v53, 0, v49, vcc
	v_cmp_le_i32_e32 vcc, v52, v198
	s_nop 1
	v_cndmask_b32_e32 v52, 0, v48, vcc
	v_mul_f32_e32 v76, v62, v52
	v_mul_f32_e32 v77, v63, v53
	v_fma_f32 v52, v86, v73, 0
	v_fmac_f32_e32 v52, v85, v78
	v_fmac_f32_e32 v52, v84, v79
	v_fmac_f32_e32 v52, v2, v80
	v_add_f32_e32 v52, v54, v52
	v_add_f32_e32 v52, v55, v52
	v_add_f32_e32 v52, v56, v52
	v_add_f32_e32 v52, v57, v52
	v_add_f32_e32 v52, v58, v52
	v_add_f32_e32 v52, v59, v52
	v_add_f32_e32 v52, v74, v52
	v_add_f32_e32 v52, v75, v52
	v_add_f32_e32 v52, v76, v52
	v_add_u32_e32 v53, 0xffffff28, v72
	v_add_f32_e32 v73, v77, v52
	v_add_u32_e32 v52, 0xffffff30, v72
	v_cmp_le_i32_e32 vcc, v53, v1
	s_nop 1
	v_cndmask_b32_e32 v53, 0, v51, vcc
	v_cmp_le_i32_e32 vcc, v52, v198
	s_nop 1
	v_cndmask_b32_e32 v52, 0, v50, vcc
	v_mul_f32_e32 v78, v60, v52
	v_mul_f32_e32 v79, v61, v53
	s_nop 0
	v_add_f32_e32 v52, v78, v73
	v_add_f32_e32 v72, v79, v52
	v_cvt_pk_bf16_f32 v52, v81, v82
	v_cvt_pk_bf16_f32 v53, v83, v87
	v_cvt_pk_bf16_f32 v54, v54, v55
	v_cvt_pk_bf16_f32 v55, v56, v57
	v_cvt_pk_bf16_f32 v56, v58, v59
	v_cvt_pk_bf16_f32 v57, v74, v75
	v_cvt_pk_bf16_f32 v58, v76, v77
	v_cvt_pk_bf16_f32 v59, v78, v79
.LBB0_729:
	s_andn2_b64 vcc, exec, s[2:3]
	s_cbranch_vccnz .LBB0_734
	s_cmp_lg_u32 s12, 2
	s_mov_b64 s[2:3], -1
	s_cbranch_scc0 .LBB0_732
	s_and_b64 s[2:3], s[6:7], exec
	s_cselect_b32 s12, 7, 5
	s_cselect_b32 s13, s77, s76
	s_and_b64 s[2:3], s[4:5], exec
	s_cselect_b32 s2, 8, s12
	s_cselect_b32 s3, s72, s13
	s_lshl_b32 s2, s40, s2
	s_add_i32 s2, s2, s3
	v_add_u32_e32 v72, s2, v232
	v_sub_co_u32_e32 v52, vcc, v198, v72
	v_cmp_gt_u32_e64 s[2:3], s1, v52
	v_add_u32_e32 v55, 9, v72
	v_add_u32_e32 v54, 8, v72
	v_cndmask_b32_e64 v52, 0, 1.0, s[2:3]
	v_add_f32_e32 v52, v52, v36
	v_cndmask_b32_e64 v73, v52, 0, vcc
	v_add_u32_e32 v52, 1, v72
	v_sub_co_u32_e32 v52, vcc, v198, v52
	v_cmp_gt_u32_e64 s[2:3], s1, v52
	v_sub_u32_e32 v56, v198, v54
	v_add_u32_e32 v57, 11, v72
	v_cndmask_b32_e64 v52, 0, 1.0, s[2:3]
	v_add_f32_e32 v52, v52, v37
	v_cndmask_b32_e64 v78, v52, 0, vcc
	v_add_u32_e32 v52, 2, v72
	v_sub_co_u32_e32 v52, vcc, v198, v52
	v_cmp_gt_u32_e64 s[2:3], s1, v52
	v_add_u32_e32 v59, 17, v72
	v_add_u32_e32 v75, 19, v72
	v_cndmask_b32_e64 v52, 0, 1.0, s[2:3]
	v_add_f32_e32 v52, v52, v38
	v_cndmask_b32_e64 v79, v52, 0, vcc
	v_add_u32_e32 v52, 3, v72
	v_sub_co_u32_e32 v52, vcc, v198, v52
	v_cmp_gt_u32_e64 s[2:3], s1, v52
	v_add_u32_e32 v77, 25, v72
	v_mul_f32_e32 v82, v85, v78
	v_cndmask_b32_e64 v52, 0, 1.0, s[2:3]
	v_add_f32_e32 v52, v52, v39
	v_cndmask_b32_e64 v80, v52, 0, vcc
	v_sub_u32_e32 v52, v1, v55
	v_cmp_gt_u32_e32 vcc, s1, v52
	v_mul_f32_e32 v81, v86, v73
	v_mul_f32_e32 v83, v84, v79
	v_cndmask_b32_e64 v53, 0, 1.0, vcc
	v_cmp_gt_u32_e32 vcc, s1, v56
	v_add_u32_e32 v56, 10, v72
	v_sub_u32_e32 v58, v198, v56
	v_cndmask_b32_e64 v52, 0, 1.0, vcc
	v_add_f32_e32 v52, v52, v40
	v_add_f32_e32 v53, v53, v41
	v_cmp_ge_u32_e32 vcc, v1, v55
	v_mul_f32_e32 v87, v2, v80
	s_mov_b64 s[2:3], 0
; __device__ __forceinline__ unsigned pk2(float lo, float hi) { return pg8::cvt_pk_bf16(lo, hi); }
; template <int RANGE>
; __device__ __forceinline__ void a_softmax(f32x16 s, int tt, int P0, int qpos, int lane, const float (&wp)[16], bf16x8& pf0, bf16x8& pf1, float& lsum) {
;     ...
;     for (int r = 0; r < 16; ++r) { const int delta = d0 - ST * ((r & 3) + 8 * (r >> 2)); float w;
;         if (RANGE == 1) w = ((unsigned)delta <= (unsigned)qpos) ? wp[r] + (delta <= 128 ? 1.f : 0.f) : 0.f;
;         else if (RANGE == 2) w = (delta <= qpos) ? wp[r] + (delta <= 512 ? 1.f : 0.f) : 0.f;
;         else w = (delta <= lim3) ? wp[r] : 0.f;
;         const float p = w * __builtin_amdgcn_exp2f(s[r]); ps += p; s[r] = p; }
;     lsum += ps;
;     v4u pa, pb; pa.x = pk2(s[0], s[1]); pa.y = pk2(s[2], s[3]); pa.z = pk2(s[4], s[5]); pa.w = pk2(s[6], s[7]); pb.x = pk2(s[8], s[9]); pb.y = pk2(s[10], s[11]); pb.z = pk2(s[12], s[13]); pb.w = pk2(s[14], s[15]);
;     pf0 = __builtin_bit_cast(bf16x8, pa); pf1 = __builtin_bit_cast(bf16x8, pb);
	v_cndmask_b32_e32 v53, 0, v53, vcc
	v_cmp_ge_u32_e32 vcc, v198, v54
	s_nop 1
	v_cndmask_b32_e32 v52, 0, v52, vcc
	v_mul_f32_e32 v54, v70, v52
	v_mul_f32_e32 v55, v71, v53
	v_sub_u32_e32 v52, v1, v57
	v_cmp_gt_u32_e32 vcc, s1, v52
	s_nop 1
	v_cndmask_b32_e64 v53, 0, 1.0, vcc
	v_cmp_gt_u32_e32 vcc, s1, v58
	v_add_u32_e32 v58, 16, v72
	v_sub_u32_e32 v74, v198, v58
	v_cndmask_b32_e64 v52, 0, 1.0, vcc
	v_add_f32_e32 v52, v52, v42
	v_add_f32_e32 v53, v53, v43
	v_cmp_ge_u32_e32 vcc, v1, v57
	s_nop 1
	v_cndmask_b32_e32 v53, 0, v53, vcc
	v_cmp_ge_u32_e32 vcc, v198, v56
	s_nop 1
	v_cndmask_b32_e32 v52, 0, v52, vcc
	v_mul_f32_e32 v56, v68, v52
	v_mul_f32_e32 v57, v69, v53
	v_sub_u32_e32 v52, v1, v59
	v_cmp_gt_u32_e32 vcc, s1, v52
	s_nop 1
	v_cndmask_b32_e64 v53, 0, 1.0, vcc
	v_cmp_gt_u32_e32 vcc, s1, v74
	v_add_u32_e32 v74, 18, v72
	v_sub_u32_e32 v76, v198, v74
	v_cndmask_b32_e64 v52, 0, 1.0, vcc
	v_add_f32_e32 v52, v52, v44
	v_add_f32_e32 v53, v53, v45
	v_cmp_ge_u32_e32 vcc, v1, v59
	s_nop 1
	v_cndmask_b32_e32 v53, 0, v53, vcc
	v_cmp_ge_u32_e32 vcc, v198, v58
	s_nop 1
	v_cndmask_b32_e32 v52, 0, v52, vcc
	v_mul_f32_e32 v58, v66, v52
	v_mul_f32_e32 v59, v67, v53
	v_sub_u32_e32 v52, v1, v75
	v_cmp_gt_u32_e32 vcc, s1, v52
	s_nop 1
	v_cndmask_b32_e64 v53, 0, 1.0, vcc
	v_cmp_gt_u32_e32 vcc, s1, v76
	v_add_u32_e32 v76, 24, v72
	v_sub_u32_e32 v88, v198, v76
	v_cndmask_b32_e64 v52, 0, 1.0, vcc
	v_add_f32_e32 v52, v52, v46
	v_add_f32_e32 v53, v53, v47
	v_cmp_ge_u32_e32 vcc, v1, v75
	s_nop 1
	v_cndmask_b32_e32 v53, 0, v53, vcc
	v_cmp_ge_u32_e32 vcc, v198, v74
	s_nop 1
	v_cndmask_b32_e32 v52, 0, v52, vcc
	v_mul_f32_e32 v74, v64, v52
	v_mul_f32_e32 v75, v65, v53
	v_sub_u32_e32 v52, v1, v77
	v_cmp_gt_u32_e32 vcc, s1, v52
	s_nop 1
	v_cndmask_b32_e64 v53, 0, 1.0, vcc
	v_cmp_gt_u32_e32 vcc, s1, v88
	s_nop 1
	v_cndmask_b32_e64 v52, 0, 1.0, vcc
	v_add_f32_e32 v52, v52, v48
	v_add_f32_e32 v53, v53, v49
	v_cmp_ge_u32_e32 vcc, v1, v77
	s_nop 1
	v_cndmask_b32_e32 v53, 0, v53, vcc
	v_cmp_ge_u32_e32 vcc, v198, v76
	s_nop 1
	v_cndmask_b32_e32 v52, 0, v52, vcc
	v_mul_f32_e32 v76, v62, v52
	v_mul_f32_e32 v77, v63, v53
	v_fma_f32 v52, v86, v73, 0
	v_fmac_f32_e32 v52, v85, v78
	v_fmac_f32_e32 v52, v84, v79
	v_fmac_f32_e32 v52, v2, v80
	v_add_f32_e32 v52, v54, v52
	v_add_f32_e32 v52, v55, v52
	v_add_f32_e32 v52, v56, v52
	v_add_f32_e32 v52, v57, v52
	v_add_f32_e32 v52, v58, v52
	v_add_f32_e32 v52, v59, v52
	v_add_f32_e32 v52, v74, v52
	v_add_f32_e32 v52, v75, v52
	v_add_f32_e32 v52, v76, v52
	v_add_u32_e32 v78, 26, v72
	v_add_u32_e32 v72, 27, v72
	v_add_f32_e32 v73, v77, v52
	v_sub_u32_e32 v52, v1, v72
	v_sub_u32_e32 v79, v198, v78
	v_cmp_gt_u32_e32 vcc, s1, v52
	s_nop 1
	v_cndmask_b32_e64 v53, 0, 1.0, vcc
	v_cmp_gt_u32_e32 vcc, s1, v79
	s_nop 1
	v_cndmask_b32_e64 v52, 0, 1.0, vcc
	v_add_f32_e32 v52, v52, v50
	v_add_f32_e32 v53, v53, v51
	v_cmp_ge_u32_e32 vcc, v1, v72
	s_nop 1
	v_cndmask_b32_e32 v53, 0, v53, vcc
	v_cmp_ge_u32_e32 vcc, v198, v78
	s_nop 1
	v_cndmask_b32_e32 v52, 0, v52, vcc
	v_mul_f32_e32 v78, v60, v52
	v_mul_f32_e32 v79, v61, v53
	s_nop 0
	v_add_f32_e32 v52, v78, v73
	v_add_f32_e32 v72, v79, v52
	v_cvt_pk_bf16_f32 v52, v81, v82
	v_cvt_pk_bf16_f32 v53, v83, v87
	v_cvt_pk_bf16_f32 v54, v54, v55
	v_cvt_pk_bf16_f32 v55, v56, v57
	v_cvt_pk_bf16_f32 v56, v58, v59
	v_cvt_pk_bf16_f32 v57, v74, v75
	v_cvt_pk_bf16_f32 v58, v76, v77
	v_cvt_pk_bf16_f32 v59, v78, v79
; __device__ __forceinline__ unsigned pk2(float lo, float hi) { return pg8::cvt_pk_bf16(lo, hi); }
; template <int RANGE>
; __device__ __forceinline__ void a_softmax(f32x16 s, int tt, int P0, int qpos, int lane, const float (&wp)[16], bf16x8& pf0, bf16x8& pf1, float& lsum) {
;     ...
;     for (int r = 0; r < 16; ++r) { const int delta = d0 - ST * ((r & 3) + 8 * (r >> 2)); float w;
;         if (RANGE == 1) w = ((unsigned)delta <= (unsigned)qpos) ? wp[r] + (delta <= 128 ? 1.f : 0.f) : 0.f;
;         else if (RANGE == 2) w = (delta <= qpos) ? wp[r] + (delta <= 512 ? 1.f : 0.f) : 0.f;
;         else w = (delta <= lim3) ? wp[r] : 0.f;
;         const float p = w * __builtin_amdgcn_exp2f(s[r]); ps += p; s[r] = p; }
;     lsum += ps;
;     v4u pa, pb; pa.x = pk2(s[0], s[1]); pa.y = pk2(s[2], s[3]); pa.z = pk2(s[4], s[5]); pa.w = pk2(s[6], s[7]); pb.x = pk2(s[8], s[9]); pb.y = pk2(s[10], s[11]); pb.z = pk2(s[12], s[13]); pb.w = pk2(s[14], s[15]);
;     pf0 = __builtin_bit_cast(bf16x8, pa); pf1 = __builtin_bit_cast(bf16x8, pb);
.LBB0_732:
	s_andn2_b64 vcc, exec, s[2:3]
	s_cbranch_vccnz .LBB0_734
	s_and_b64 s[2:3], s[6:7], exec
	s_cselect_b32 s6, 0xffffff80, s91
	s_cselect_b32 s7, 0x500, s0
	s_and_b64 s[2:3], s[4:5], exec
	s_cselect_b32 s2, 0xffffff00, s6
	s_cselect_b32 s3, 0x800, s7
	s_mul_i32 s2, s2, s40
	v_subrev_u32_e32 v52, s10, v198
	s_add_i32 s2, s2, s3
	v_add_u32_e32 v52, s2, v52
	v_sub_u32_e32 v53, v52, v230
	v_cmp_gt_i32_e32 vcc, s68, v53
	s_nop 1
	v_cndmask_b32_e64 v54, 0, 1.0, vcc
	v_add_f32_e32 v36, v54, v36
	v_cmp_le_i32_e32 vcc, v53, v198
	s_nop 1
	v_cndmask_b32_e32 v54, 0, v36, vcc
	v_sub_u32_e32 v36, v52, v229
	v_cmp_gt_i32_e32 vcc, s68, v36
	v_mul_f32_e32 v57, v86, v54
	s_nop 0
	v_cndmask_b32_e64 v55, 0, 1.0, vcc
	v_add_f32_e32 v37, v55, v37
	v_cmp_le_i32_e32 vcc, v36, v198
	v_sub_u32_e32 v36, v52, v227
	s_nop 0
	v_cndmask_b32_e32 v55, 0, v37, vcc
	v_cmp_gt_i32_e32 vcc, s68, v36
	v_mul_f32_e32 v58, v85, v55
	s_nop 0
	v_cndmask_b32_e64 v37, 0, 1.0, vcc
	v_add_f32_e32 v37, v37, v38
	v_cmp_le_i32_e32 vcc, v36, v198
	v_sub_u32_e32 v36, v52, v225
	v_subrev_u32_e32 v38, 36, v53
	v_cndmask_b32_e32 v56, 0, v37, vcc
	v_cmp_gt_i32_e32 vcc, s68, v36
	v_mul_f32_e32 v59, v84, v56
	s_nop 0
	v_cndmask_b32_e64 v37, 0, 1.0, vcc
	v_add_f32_e32 v37, v37, v39
	v_cmp_le_i32_e32 vcc, v36, v198
	v_subrev_u32_e32 v39, 32, v53
	s_nop 0
	v_cndmask_b32_e32 v52, 0, v37, vcc
	v_cmp_gt_i32_e32 vcc, s68, v38
	v_mul_f32_e32 v73, v2, v52
	s_nop 0
	v_cndmask_b32_e64 v37, 0, 1.0, vcc
	v_cmp_gt_i32_e32 vcc, s68, v39
	s_nop 1
	v_cndmask_b32_e64 v36, 0, 1.0, vcc
	v_add_f32_e32 v36, v36, v40
	v_add_f32_e32 v37, v37, v41
	v_cmp_le_i32_e32 vcc, v38, v1
	v_subrev_u32_e32 v40, 44, v53
	v_subrev_u32_e32 v41, 40, v53
	v_cndmask_b32_e32 v37, 0, v37, vcc
	v_cmp_le_i32_e32 vcc, v39, v198
	s_nop 1
	v_cndmask_b32_e32 v36, 0, v36, vcc
	v_cmp_gt_i32_e32 vcc, s68, v40
	v_mul_f32_e32 v36, v70, v36
	v_mul_f32_e32 v37, v71, v37
	s_nop 0
	v_cndmask_b32_e64 v39, 0, 1.0, vcc
	v_cmp_gt_i32_e32 vcc, s68, v41
	s_nop 1
	v_cndmask_b32_e64 v38, 0, 1.0, vcc
	v_add_f32_e32 v38, v38, v42
	v_add_f32_e32 v39, v39, v43
	v_cmp_le_i32_e32 vcc, v40, v1
	v_add_u32_e32 v42, 0xffffffbc, v53
	v_subrev_u32_e32 v43, 64, v53
	v_cndmask_b32_e32 v39, 0, v39, vcc
	v_cmp_le_i32_e32 vcc, v41, v198
	s_nop 1
	v_cndmask_b32_e32 v38, 0, v38, vcc
	v_cmp_gt_i32_e32 vcc, s68, v42
	v_mul_f32_e32 v38, v68, v38
	v_mul_f32_e32 v39, v69, v39
	s_nop 0
	v_cndmask_b32_e64 v41, 0, 1.0, vcc
	v_cmp_gt_i32_e32 vcc, s68, v43
	s_nop 1
	v_cndmask_b32_e64 v40, 0, 1.0, vcc
	v_add_f32_e32 v40, v40, v44
	v_add_f32_e32 v41, v41, v45
	v_cmp_le_i32_e32 vcc, v42, v1
	v_add_u32_e32 v44, 0xffffffb4, v53
	v_add_u32_e32 v45, 0xffffffb8, v53
	v_cndmask_b32_e32 v41, 0, v41, vcc
	v_cmp_le_i32_e32 vcc, v43, v198
	s_nop 1
	v_cndmask_b32_e32 v40, 0, v40, vcc
	v_cmp_gt_i32_e32 vcc, s68, v44
	v_mul_f32_e32 v40, v66, v40
	v_mul_f32_e32 v41, v67, v41
	s_nop 0
	v_cndmask_b32_e64 v43, 0, 1.0, vcc
	v_cmp_gt_i32_e32 vcc, s68, v45
	s_nop 1
	v_cndmask_b32_e64 v42, 0, 1.0, vcc
	v_add_f32_e32 v42, v42, v46
	v_add_f32_e32 v43, v43, v47
	v_cmp_le_i32_e32 vcc, v44, v1
	v_add_u32_e32 v46, 0xffffff9c, v53
	v_add_u32_e32 v47, 0xffffffa0, v53
	v_cndmask_b32_e32 v43, 0, v43, vcc
	v_cmp_le_i32_e32 vcc, v45, v198
	s_nop 1
	v_cndmask_b32_e32 v42, 0, v42, vcc
	v_cmp_gt_i32_e32 vcc, s68, v46
	v_mul_f32_e32 v42, v64, v42
	v_mul_f32_e32 v43, v65, v43
	s_nop 0
	v_cndmask_b32_e64 v45, 0, 1.0, vcc
	v_cmp_gt_i32_e32 vcc, s68, v47
	s_nop 1
	v_cndmask_b32_e64 v44, 0, 1.0, vcc
	v_cmp_le_i32_e32 vcc, v46, v1
	v_fma_f32 v46, v86, v54, 0
	v_fmac_f32_e32 v46, v85, v55
	v_fmac_f32_e32 v46, v84, v56
	v_fmac_f32_e32 v46, v2, v52
	v_add_f32_e32 v2, v36, v46
	v_add_f32_e32 v44, v44, v48
	v_add_f32_e32 v45, v45, v49
	v_add_f32_e32 v2, v37, v2
	v_cndmask_b32_e32 v45, 0, v45, vcc
	v_cmp_le_i32_e32 vcc, v47, v198
	v_add_f32_e32 v2, v38, v2
	v_add_u32_e32 v48, 0xffffff94, v53
	v_cndmask_b32_e32 v44, 0, v44, vcc
	v_add_f32_e32 v2, v39, v2
	v_add_u32_e32 v49, 0xffffff98, v53
	v_cmp_gt_i32_e32 vcc, s68, v48
	v_add_f32_e32 v2, v40, v2
	v_add_f32_e32 v2, v41, v2
	v_cndmask_b32_e64 v47, 0, 1.0, vcc
	v_cmp_gt_i32_e32 vcc, s68, v49
	v_add_f32_e32 v2, v42, v2
	v_mul_f32_e32 v44, v62, v44
	v_mul_f32_e32 v45, v63, v45
	v_cndmask_b32_e64 v46, 0, 1.0, vcc
	v_add_f32_e32 v46, v46, v50
	v_add_f32_e32 v47, v47, v51
	v_cmp_le_i32_e32 vcc, v48, v1
	v_add_f32_e32 v2, v43, v2
	v_add_f32_e32 v2, v44, v2
	v_cndmask_b32_e32 v47, 0, v47, vcc
	v_cmp_le_i32_e32 vcc, v49, v198
	v_add_f32_e32 v2, v45, v2
	v_cvt_pk_bf16_f32 v52, v57, v58
	v_cvt_pk_bf16_f32 v53, v59, v73
	v_cvt_pk_bf16_f32 v54, v36, v37
	v_cvt_pk_bf16_f32 v55, v38, v39
	s_nop 0
	v_cndmask_b32_e32 v46, 0, v46, vcc
	v_mul_f32_e32 v46, v60, v46
	v_mul_f32_e32 v47, v61, v47
	v_cvt_pk_bf16_f32 v56, v40, v41
	v_cvt_pk_bf16_f32 v57, v42, v43
	v_cvt_pk_bf16_f32 v58, v44, v45
	s_nop 0
	v_add_f32_e32 v1, v46, v2
	v_add_f32_e32 v72, v47, v1
	v_cvt_pk_bf16_f32 v59, v46, v47
